# FoX unit prologue: cum-table loads issued at the unit header with the Q loads (wave-uniform validity), table filled right after the pref barrier; replaces the chunked load-wait loop
# speedup vs baseline: 1.0295x; 1.0001x over previous
.Lq_p1:
	s_lshr_b32 s95, s88, 3
	s_lshl_b32 s95, s95, 14
	s_add_u32 s96, s38, s95
	s_addc_u32 s97, s39, 0
	v_lshlrev_b32_e32 v253, 2, v255
	v_readfirstlane_b32 s95, v255
	s_lshl_b32 s89, s94, 8
	s_addk_i32 s89, 0x100
	s_cmp_lt_u32 s95, s89
	s_cbranch_scc0 .Lq_cl_done
	global_load_dword v242, v253, s[96:97]
	s_addk_i32 s95, 0x200
	s_cmp_lt_u32 s95, s89
	s_cbranch_scc0 .Lq_cl_done
	global_load_dword v243, v253, s[96:97] offset:2048
	s_addk_i32 s95, 0x200
	v_add_u32_e32 v253, 0x1000, v253
	s_cmp_lt_u32 s95, s89
	s_cbranch_scc0 .Lq_cl_done
	global_load_dword v244, v253, s[96:97]
	s_addk_i32 s95, 0x200
	s_cmp_lt_u32 s95, s89
	s_cbranch_scc0 .Lq_cl_done
	global_load_dword v245, v253, s[96:97] offset:2048
	s_addk_i32 s95, 0x200
	v_add_u32_e32 v253, 0x1000, v253
	s_cmp_lt_u32 s95, s89
	s_cbranch_scc0 .Lq_cl_done
	global_load_dword v246, v253, s[96:97]
	s_addk_i32 s95, 0x200
	s_cmp_lt_u32 s95, s89
	s_cbranch_scc0 .Lq_cl_done
	global_load_dword v247, v253, s[96:97] offset:2048
	s_addk_i32 s95, 0x200
	v_add_u32_e32 v253, 0x1000, v253
	s_cmp_lt_u32 s95, s89
	s_cbranch_scc0 .Lq_cl_done
	global_load_dword v248, v253, s[96:97]
	s_addk_i32 s95, 0x200
	s_cmp_lt_u32 s95, s89
	s_cbranch_scc0 .Lq_cl_done
	global_load_dword v249, v253, s[96:97] offset:2048

.LBB0_628:
	s_lshl_b32 s6, s0, 4
	s_lshr_b32 s1, s88, 3
	s_or_b32 s0, s6, s4
	s_and_b32 s5, s1, 15
	s_ashr_i32 s1, s0, 31
	s_lshl_b32 s16, s4, 7
	s_lshl_b64 s[0:1], s[0:1], 14
	s_add_u32 s26, s38, s0
	s_addc_u32 s27, s39, s1
	s_or_b32 s0, s6, s5
	s_ashr_i32 s1, s0, 31
	s_add_i32 s61, s60, 0x100
	s_lshl_b64 s[0:1], s[0:1], 14
	s_add_u32 s0, s40, s0
	s_addc_u32 s1, s41, s1
	v_lshl_add_u64 v[24:25], v[18:19], 2, s[0:1]
	v_lshl_add_u32 v19, v18, 2, s44
	s_mov_b32 s62, 0
	s_waitcnt lgkmcnt(0)
	s_barrier
	v_lshrrev_b32_e32 v252, 6, v255
	v_lshlrev_b32_e32 v252, 2, v252
	v_add_u32_e32 v252, 0x16800, v252
	ds_read_b32 v234, v252
	ds_read_b32 v235, v252 offset:32
	ds_read_b32 v236, v252 offset:64
	ds_read_b32 v237, v252 offset:96
	ds_read_b32 v238, v252 offset:128
	ds_read_b32 v239, v252 offset:160
	ds_read_b32 v240, v252 offset:192
	ds_read_b32 v241, v252 offset:224
	v_lshl_add_u32 v253, v255, 2, s44
	v_readfirstlane_b32 s95, v255
	s_waitcnt vmcnt(0) lgkmcnt(0)
	s_cmp_lt_u32 s95, s89
	s_cbranch_scc0 .Lq_fill_done
	v_add_f32_e32 v242, v242, v234
	v_mul_f32_e32 v242, 0xbfb8aa3b, v242
	ds_write_b32 v253, v242
	s_addk_i32 s95, 0x200
	s_cmp_lt_u32 s95, s89
	s_cbranch_scc0 .Lq_fill_done
	v_add_f32_e32 v243, v243, v235
	v_mul_f32_e32 v243, 0xbfb8aa3b, v243
	ds_write_b32 v253, v243 offset:2048
	s_addk_i32 s95, 0x200
	s_cmp_lt_u32 s95, s89
	s_cbranch_scc0 .Lq_fill_done
	v_add_f32_e32 v244, v244, v236
	v_mul_f32_e32 v244, 0xbfb8aa3b, v244
	ds_write_b32 v253, v244 offset:4096
	s_addk_i32 s95, 0x200
	s_cmp_lt_u32 s95, s89
	s_cbranch_scc0 .Lq_fill_done
	v_add_f32_e32 v245, v245, v237
	v_mul_f32_e32 v245, 0xbfb8aa3b, v245
	ds_write_b32 v253, v245 offset:6144
	s_addk_i32 s95, 0x200
	s_cmp_lt_u32 s95, s89
	s_cbranch_scc0 .Lq_fill_done
	v_add_f32_e32 v246, v246, v238
	v_mul_f32_e32 v246, 0xbfb8aa3b, v246
	ds_write_b32 v253, v246 offset:8192
	s_addk_i32 s95, 0x200
	s_cmp_lt_u32 s95, s89
	s_cbranch_scc0 .Lq_fill_done
	v_add_f32_e32 v247, v247, v239
	v_mul_f32_e32 v247, 0xbfb8aa3b, v247
	ds_write_b32 v253, v247 offset:10240
	s_addk_i32 s95, 0x200
	s_cmp_lt_u32 s95, s89
	s_cbranch_scc0 .Lq_fill_done
	v_add_f32_e32 v248, v248, v240
	v_mul_f32_e32 v248, 0xbfb8aa3b, v248
	ds_write_b32 v253, v248 offset:12288
	s_addk_i32 s95, 0x200
	s_cmp_lt_u32 s95, s89
	s_cbranch_scc0 .Lq_fill_done
	v_add_f32_e32 v249, v249, v241
	v_mul_f32_e32 v249, 0xbfb8aa3b, v249
	ds_write_b32 v253, v249 offset:14336
.Lq_fill_done:
.LBB0_646:
	v_mul_lo_u32 v157, v146, s45
	v_lshlrev_b32_e32 v158, 4, v0
	v_add3_u32 v0, 0, v157, v158
	s_waitcnt vmcnt(0)
	v_readfirstlane_b32 s96, v255
	s_cmp_lg_u32 s96, 0
	s_cbranch_scc1 .Lq_w1
	s_mov_b64 s[96:97], exec
	s_mov_b64 exec, 1
	s_lshl_b32 s95, s92, 8
	v_or_b32_e32 v251, s95, v250
	v_mov_b32_e32 v253, 0x40000000
	v_cmp_gt_u32_e32 vcc, 0x80, v250
	v_mov_b32_e32 v252, 0x1c000
	v_cndmask_b32_e32 v251, v253, v251, vcc
	ds_write_b32 v252, v251
	s_mov_b64 exec, s[96:97]
